# combined exact micro-edits on v15: norm mod-row sharing, samp_b bias hoist, attn PV read-ahead, h3 cross-barrier prefetch, DPP for h3/attn reductions
# speedup vs baseline: 1.0051x; 1.0051x over previous
.LBB0_300:
	s_waitcnt lgkmcnt(0)
	s_barrier
	ds_read_b128 v[0:3], v144
	ds_read_b128 v[4:7], v145
	ds_read_b128 v[150:153], v144 offset:32
	ds_read_b128 v[154:157], v145 offset:32
	s_waitcnt lgkmcnt(2)
	v_mfma_f32_32x32x16_bf16 v[0:15], v[0:3], v[4:7], 0
	v_add_u32_e32 v97, 0x2400, v147
	v_add_u32_e32 v107, 0x3000, v147
	v_readlane_b32 s0, v251, 57
	v_readlane_b32 s1, v251, 58
	s_cmpk_gt_i32 s4, 0x3ff
	s_waitcnt lgkmcnt(0)
	v_mfma_f32_32x32x16_bf16 v[0:15], v[150:153], v[154:157], v[0:15]
	ds_read_b128 v[150:153], v144 offset:64
	ds_read_b128 v[154:157], v145 offset:64
	s_waitcnt lgkmcnt(0)
	v_mfma_f32_32x32x16_bf16 v[0:15], v[150:153], v[154:157], v[0:15]
	ds_read_b128 v[150:153], v144 offset:96
	ds_read_b128 v[154:157], v145 offset:96
	s_waitcnt lgkmcnt(0)
	v_mfma_f32_32x32x16_bf16 v[0:15], v[150:153], v[154:157], v[0:15]
	ds_read_b128 v[150:153], v146 offset:65280
	s_waitcnt vmcnt(13) lgkmcnt(0)
	v_mfma_f32_32x32x16_bf16 v[0:15], v[150:153], v[68:71], v[0:15]
	ds_read_b128 v[68:71], v146 offset:65312
	s_waitcnt vmcnt(12) lgkmcnt(0)
	v_mfma_f32_32x32x16_bf16 v[0:15], v[68:71], v[64:67], v[0:15]
	ds_read_b128 v[64:67], v146 offset:65344
	ds_read_b128 v[68:71], v146 offset:65376
	ds_read_b128 v[150:153], v146 offset:65408
	ds_read_b128 v[154:157], v146 offset:65440
	ds_read_b128 v[158:161], v146 offset:65472
	s_waitcnt vmcnt(11) lgkmcnt(4)
	v_mfma_f32_32x32x16_bf16 v[0:15], v[64:67], v[60:63], v[0:15]
	ds_read_b128 v[60:63], v146 offset:65504
	v_add_u32_e32 v64, 0x400, v147
	v_add_u32_e32 v65, 0x1000, v147
	v_add_u32_e32 v66, 0x1400, v147
	v_add_u32_e32 v67, 0x2000, v147
	s_waitcnt vmcnt(10) lgkmcnt(4)
	v_mfma_f32_32x32x16_bf16 v[0:15], v[68:71], v[56:59], v[0:15]
	v_add_u32_e32 v68, 0x3400, v147
	v_lshlrev_b32_e32 v56, 16, v44
	v_and_b32_e32 v57, 0xffff0000, v44
	v_lshlrev_b32_e32 v44, 16, v45
	v_and_b32_e32 v45, 0xffff0000, v45
	v_lshlrev_b32_e32 v58, 16, v46
	v_and_b32_e32 v59, 0xffff0000, v46
	s_waitcnt vmcnt(9) lgkmcnt(3)
	v_mfma_f32_32x32x16_bf16 v[0:15], v[150:153], v[52:55], v[0:15]
	v_mul_f32_e32 v52, 0xbfb8aa3b, v56
	v_mul_f32_e32 v53, 0xbfb8aa3b, v57
	v_mul_f32_e32 v54, 0xbfb8aa3b, v44
	v_lshlrev_b32_e32 v46, 16, v47
	v_and_b32_e32 v47, 0xffff0000, v47
	v_mul_f32_e32 v55, 0xbfb8aa3b, v45
	v_mul_f32_e32 v69, 0xbfb8aa3b, v58
	s_waitcnt vmcnt(8) lgkmcnt(2)
	v_mfma_f32_32x32x16_bf16 v[0:15], v[154:157], v[48:51], v[0:15]
	v_exp_f32_e32 v51, v52
	v_exp_f32_e32 v52, v53
	v_exp_f32_e32 v53, v54
	v_mul_f32_e32 v48, 0xbfb8aa3b, v59
	v_mul_f32_e32 v50, 0xbfb8aa3b, v47
	v_add_f32_e32 v149, 1.0, v52
	v_add_f32_e32 v150, 1.0, v53
	s_waitcnt vmcnt(7) lgkmcnt(1)
	v_mfma_f32_32x32x16_bf16 v[0:15], v[158:161], v[40:43], v[0:15]
	v_mul_f32_e32 v49, 0xbfb8aa3b, v46
	v_exp_f32_e32 v54, v55
	v_exp_f32_e32 v55, v69
	v_exp_f32_e32 v69, v48
	v_exp_f32_e32 v71, v50
	v_add_f32_e32 v51, 1.0, v51
	v_exp_f32_e32 v70, v49
	s_waitcnt vmcnt(6) lgkmcnt(0)
	v_mfma_f32_32x32x16_bf16 v[0:15], v[60:63], v[36:39], v[0:15]
	v_add_f32_e32 v54, 1.0, v54
	s_nop 10
	ds_write2_b32 v147, v0, v1 offset1:132
	ds_write2_b32 v64, v2, v3 offset0:8 offset1:140
	ds_write2_b32 v65, v4, v5 offset0:32 offset1:164
	ds_write2_b32 v66, v6, v7 offset0:40 offset1:172
	ds_write2_b32 v67, v8, v9 offset0:64 offset1:196
	ds_write2_b32 v97, v10, v11 offset0:72 offset1:204
	ds_write2_b32 v107, v12, v13 offset0:96 offset1:228
	ds_write2_b32 v68, v14, v15 offset0:104 offset1:236
	s_waitcnt lgkmcnt(0)
	s_barrier
	ds_read_b128 v[0:3], v148
	ds_read_b128 v[4:7], v148 offset:16
	ds_read_b128 v[8:11], v148 offset:32
	ds_read_b128 v[12:15], v148 offset:48
	v_mov_b32_e32 v107, v209
	s_waitcnt lgkmcnt(2)
	v_pk_mul_f32 v[40:41], v[6:7], v[6:7]
	v_pk_mul_f32 v[36:37], v[2:3], v[2:3]
	v_pk_mul_f32 v[38:39], v[0:1], v[0:1]
	v_pk_mul_f32 v[42:43], v[4:5], v[4:5]
	v_pk_mov_b32 v[52:53], v[38:39], v[36:37] op_sel:[1,0]
	v_mov_b32_e32 v39, v37
	v_pk_mov_b32 v[36:37], v[42:43], v[40:41] op_sel:[1,0]
	v_mov_b32_e32 v43, v41
	s_waitcnt lgkmcnt(1)
	v_mul_f32_e32 v48, v9, v9
	v_mul_f32_e32 v50, v11, v11
	v_pk_add_f32 v[38:39], v[52:53], v[38:39]
	v_pk_add_f32 v[36:37], v[36:37], v[42:43]
	s_waitcnt lgkmcnt(0)
	v_mul_f32_e32 v60, v12, v12
	v_mul_f32_e32 v61, v13, v13
	v_mul_f32_e32 v62, v14, v14
	v_mul_f32_e32 v63, v15, v15
	v_pk_fma_f32 v[40:41], v[8:9], v[8:9], v[48:49] op_sel_hi:[1,1,0]
	v_pk_fma_f32 v[48:49], v[10:11], v[10:11], v[50:51] op_sel_hi:[1,1,0]
	v_pk_add_f32 v[38:39], v[38:39], v[38:39] op_sel:[0,1] op_sel_hi:[1,0]
	v_pk_add_f32 v[36:37], v[36:37], v[36:37] op_sel:[0,1] op_sel_hi:[1,0]
	v_mov_b32_e32 v41, v62
	v_mov_b32_e32 v49, v63
	v_mov_b32_e32 v39, v60
	v_mov_b32_e32 v37, v61
	v_pk_add_f32 v[40:41], v[40:41], v[48:49]
	v_pk_add_f32 v[36:37], v[38:39], v[36:37]
	v_rcp_f32_e32 v38, v150
	v_pk_add_f32 v[36:37], v[36:37], v[40:41]
	v_rcp_f32_e32 v39, v54
	v_add_f32_e32 v36, v36, v37
	s_nop 1
	v_mov_b32_dpp v37, v36 quad_perm:[1,0,3,2] row_mask:0xf bank_mask:0xf
	v_add_f32_e32 v40, 1.0, v55
	v_add_f32_e32 v41, 1.0, v69
	v_pk_mul_f32 v[38:39], v[38:39], v[44:45]
	v_rcp_f32_e32 v40, v40
	s_waitcnt lgkmcnt(0)
	v_add_f32_e32 v48, v36, v37
	s_nop 1
	v_mov_b32_dpp v49, v48 quad_perm:[2,3,0,1] row_mask:0xf bank_mask:0xf
	v_rcp_f32_e32 v36, v51
	v_rcp_f32_e32 v37, v149
	v_rcp_f32_e32 v41, v41
	v_add_f32_e32 v42, 1.0, v70
	s_waitcnt lgkmcnt(0)
	v_add_f32_e32 v48, v48, v49
	s_nop 1
	v_mov_b32_dpp v49, v48 row_half_mirror row_mask:0xf bank_mask:0xf
	v_pk_mul_f32 v[36:37], v[36:37], v[56:57]
	v_add_f32_e32 v43, 1.0, v71
	v_rcp_f32_e32 v42, v42
	v_rcp_f32_e32 v43, v43
	s_waitcnt lgkmcnt(0)
	v_add_f32_e32 v48, v48, v49
	v_fmamk_f32 v48, v48, 0x3c000000, v222
	v_rsq_f32_e32 v48, v48
	v_pk_mul_f32 v[40:41], v[40:41], v[58:59]
	v_pk_mul_f32 v[0:1], v[0:1], v[48:49] op_sel_hi:[1,0]
	v_pk_mul_f32 v[2:3], v[2:3], v[48:49] op_sel_hi:[1,0]
	v_pk_mul_f32 v[4:5], v[4:5], v[48:49] op_sel_hi:[1,0]
	v_pk_mul_f32 v[0:1], v[32:33], v[0:1]
	v_pk_mul_f32 v[2:3], v[34:35], v[2:3]
	v_pk_mul_f32 v[4:5], v[28:29], v[4:5]
	v_pk_mul_f32 v[0:1], v[36:37], v[0:1]
	v_pk_mul_f32 v[2:3], v[38:39], v[2:3]
	v_lshlrev_b32_e32 v28, 16, v24
	v_cvt_pk_bf16_f32 v0, v0, v1
	v_cvt_pk_bf16_f32 v1, v2, v3
	v_and_b32_e32 v29, 0xffff0000, v24
	v_mul_f32_e32 v3, 0xbfb8aa3b, v28
	v_exp_f32_e32 v3, v3
	v_mul_f32_e32 v24, 0xbfb8aa3b, v29
	v_exp_f32_e32 v24, v24
	v_pk_mul_f32 v[6:7], v[6:7], v[48:49] op_sel_hi:[1,0]
	v_pk_mul_f32 v[4:5], v[40:41], v[4:5]
	v_add_f32_e32 v3, 1.0, v3
	v_cvt_pk_bf16_f32 v2, v4, v5
	v_pk_mul_f32 v[4:5], v[30:31], v[6:7]
	v_pk_mul_f32 v[6:7], v[42:43], v[46:47]
	v_pk_mul_f32 v[10:11], v[10:11], v[48:49] op_sel_hi:[1,0]
	v_pk_mul_f32 v[4:5], v[6:7], v[4:5]
	v_rcp_f32_e32 v6, v3
	v_add_f32_e32 v3, 1.0, v24
	v_rcp_f32_e32 v7, v3
	v_cvt_pk_bf16_f32 v3, v4, v5
	v_pk_mul_f32 v[4:5], v[8:9], v[48:49] op_sel_hi:[1,0]
	v_lshlrev_b32_e32 v8, 16, v25
	v_and_b32_e32 v9, 0xffff0000, v25
	v_pk_mul_f32 v[4:5], v[20:21], v[4:5]
	v_mul_f32_e32 v20, 0xbfb8aa3b, v8
	v_mul_f32_e32 v21, 0xbfb8aa3b, v9
	v_exp_f32_e32 v20, v20
	v_exp_f32_e32 v21, v21
	v_pk_mul_f32 v[6:7], v[6:7], v[28:29]
	v_pk_mul_f32 v[10:11], v[22:23], v[10:11]
	v_pk_mul_f32 v[4:5], v[6:7], v[4:5]
	v_add_f32_e32 v6, 1.0, v20
	v_add_f32_e32 v7, 1.0, v21
	v_rcp_f32_e32 v6, v6
	v_rcp_f32_e32 v7, v7
	v_cvt_pk_bf16_f32 v4, v4, v5
	v_pk_mul_f32 v[6:7], v[6:7], v[8:9]
	v_lshlrev_b32_e32 v8, 16, v26
	v_and_b32_e32 v9, 0xffff0000, v26
	v_mul_f32_e32 v5, 0xbfb8aa3b, v8
	v_exp_f32_e32 v5, v5
	v_mul_f32_e32 v20, 0xbfb8aa3b, v9
	v_exp_f32_e32 v20, v20
	v_pk_mul_f32 v[6:7], v[6:7], v[10:11]
	v_add_f32_e32 v5, 1.0, v5
	v_rcp_f32_e32 v10, v5
	v_add_f32_e32 v5, 1.0, v20
	v_rcp_f32_e32 v11, v5
	v_cvt_pk_bf16_f32 v5, v6, v7
	v_pk_mul_f32 v[6:7], v[12:13], v[48:49] op_sel_hi:[1,0]
	v_pk_mul_f32 v[8:9], v[10:11], v[8:9]
	v_lshlrev_b32_e32 v10, 16, v27
	v_and_b32_e32 v11, 0xffff0000, v27
	v_mul_f32_e32 v12, 0xbfb8aa3b, v10
	v_mul_f32_e32 v13, 0xbfb8aa3b, v11
	v_exp_f32_e32 v12, v12
	v_exp_f32_e32 v13, v13
	v_pk_mul_f32 v[6:7], v[16:17], v[6:7]
	s_nop 0
	v_pk_mul_f32 v[6:7], v[8:9], v[6:7]
	v_add_f32_e32 v8, 1.0, v12
	v_add_f32_e32 v9, 1.0, v13
	v_rcp_f32_e32 v8, v8
	v_rcp_f32_e32 v9, v9
	v_pk_mul_f32 v[12:13], v[14:15], v[48:49] op_sel_hi:[1,0]
	v_cvt_pk_bf16_f32 v6, v6, v7
	v_pk_mul_f32 v[12:13], v[18:19], v[12:13]
	v_pk_mul_f32 v[8:9], v[8:9], v[10:11]
	s_nop 0
	v_pk_mul_f32 v[8:9], v[8:9], v[12:13]
	s_nop 0
	v_cvt_pk_bf16_f32 v7, v8, v9
	v_lshlrev_b64 v[8:9], 11, v[108:109]
	v_lshl_add_u64 v[8:9], s[0:1], 0, v[8:9]
	v_lshl_add_u64 v[8:9], v[8:9], 0, s[54:55]
	v_lshl_add_u64 v[8:9], v[8:9], 0, v[106:107]
	s_mov_b64 s[0:1], 0xbe00200
	v_lshl_add_u64 v[10:11], v[8:9], 0, s[0:1]
	v_add_co_u32_e32 v8, vcc, 0xbe00000, v8
	global_store_dwordx4 v[10:11], v[4:7], off offset:16
	s_nop 0
	v_addc_co_u32_e32 v9, vcc, 0, v9, vcc
	global_store_dwordx4 v[8:9], v[0:3], off offset:512
	s_cbranch_scc1 .LBB0_398

.LBB0_468:
	s_or_b64 exec, exec, s[20:21]
	v_add_u32_e32 v98, 0x8480, v152
	v_add_u32_e32 v100, 0x8488, v152
	v_add_u32_e32 v102, 0x84a0, v152
	v_add_u32_e32 v104, 0x84a8, v152
	s_waitcnt lgkmcnt(0)
	s_barrier
	ds_read2_b32 v[98:99], v98 offset1:1
	ds_read2_b32 v[100:101], v100 offset1:1
	ds_read2_b32 v[102:103], v102 offset1:1
	ds_read2_b32 v[104:105], v104 offset1:1
	v_readlane_b32 s20, v253, 47
	v_add_u32_e32 v106, 0x84c0, v152
	v_add_u32_e32 v108, 0x84c8, v152
	v_add_u32_e32 v110, 0x84e0, v152
	v_add_u32_e32 v112, 0x84e8, v152
	v_readlane_b32 s21, v253, 48
	ds_read2_b32 v[106:107], v106 offset1:1
	ds_read2_b32 v[108:109], v108 offset1:1
	ds_read2_b32 v[110:111], v110 offset1:1
	ds_read2_b32 v[112:113], v112 offset1:1
	s_waitcnt lgkmcnt(6)
	s_and_b64 vcc, s[20:21], s[44:45]
	v_readlane_b32 s20, v253, 49
	v_fmac_f32_e32 v98, 0x3e000000, v64
	v_readlane_b32 s21, v253, 50
	v_cndmask_b32_e32 v64, v228, v98, vcc
	v_fmac_f32_e32 v99, 0x3e000000, v65
	s_and_b64 vcc, s[20:21], s[44:45]
	v_cndmask_b32_e32 v65, v228, v99, vcc
	s_mov_b32 s20, 0xff800000
	v_max3_f32 v98, v64, s20, v65
	v_readlane_b32 s20, v253, 51
	v_readlane_b32 s21, v253, 52
	s_and_b64 vcc, s[20:21], s[44:45]
	v_readlane_b32 s20, v253, 53
	v_fmac_f32_e32 v100, 0x3e000000, v66
	v_readlane_b32 s21, v253, 54
	v_cndmask_b32_e32 v66, v228, v100, vcc
	s_and_b64 vcc, s[20:21], s[44:45]
	v_readlane_b32 s20, v253, 55
	v_fmac_f32_e32 v101, 0x3e000000, v67
	v_readlane_b32 s21, v253, 56
	s_waitcnt lgkmcnt(4)
	v_cndmask_b32_e32 v67, v228, v101, vcc
	s_and_b64 vcc, s[20:21], s[44:45]
	v_readlane_b32 s20, v253, 57
	v_fmac_f32_e32 v102, 0x3e000000, v68
	v_readlane_b32 s21, v253, 58
	v_cndmask_b32_e32 v68, v228, v102, vcc
	s_and_b64 vcc, s[20:21], s[44:45]
	v_readlane_b32 s20, v253, 59
	v_fmac_f32_e32 v103, 0x3e000000, v69
	v_readlane_b32 s21, v253, 60
	v_cndmask_b32_e32 v69, v228, v103, vcc
	s_and_b64 vcc, s[20:21], s[44:45]
	v_readlane_b32 s20, v253, 61
	v_fmac_f32_e32 v104, 0x3e000000, v70
	v_readlane_b32 s21, v253, 62
	v_cndmask_b32_e32 v70, v228, v104, vcc
	s_and_b64 vcc, s[20:21], s[44:45]
	v_readlane_b32 s20, v253, 63
	v_fmac_f32_e32 v105, 0x3e000000, v71
	v_readlane_b32 s21, v254, 0
	s_waitcnt lgkmcnt(2)
	v_cndmask_b32_e32 v71, v228, v105, vcc
	s_and_b64 vcc, s[20:21], s[44:45]
	v_readlane_b32 s20, v254, 1
	v_fmac_f32_e32 v106, 0x3e000000, v72
	v_readlane_b32 s21, v254, 2
	v_cndmask_b32_e32 v72, v228, v106, vcc
	s_and_b64 vcc, s[20:21], s[44:45]
	v_readlane_b32 s20, v254, 3
	v_fmac_f32_e32 v107, 0x3e000000, v73
	v_readlane_b32 s21, v254, 4
	v_cndmask_b32_e32 v73, v228, v107, vcc
	s_and_b64 vcc, s[20:21], s[44:45]
	v_readlane_b32 s20, v254, 5
	v_fmac_f32_e32 v108, 0x3e000000, v74
	v_readlane_b32 s21, v254, 6
	v_max3_f32 v98, v98, v66, v67
	v_cndmask_b32_e32 v74, v228, v108, vcc
	s_and_b64 vcc, s[20:21], s[44:45]
	v_readlane_b32 s20, v254, 7
	v_max3_f32 v98, v98, v68, v69
	v_fmac_f32_e32 v109, 0x3e000000, v75
	v_readlane_b32 s21, v254, 8
	s_waitcnt lgkmcnt(0)
	v_max3_f32 v98, v98, v70, v71
	v_cndmask_b32_e32 v75, v228, v109, vcc
	s_and_b64 vcc, s[20:21], s[44:45]
	v_readlane_b32 s20, v254, 9
	v_max3_f32 v98, v98, v72, v73
	v_fmac_f32_e32 v110, 0x3e000000, v76
	v_readlane_b32 s21, v254, 10
	v_max3_f32 v99, v98, v74, v75
	v_cndmask_b32_e32 v98, v228, v110, vcc
	s_and_b64 vcc, s[20:21], s[44:45]
	v_readlane_b32 s20, v254, 11
	v_fmac_f32_e32 v111, 0x3e000000, v77
	v_readlane_b32 s21, v254, 12
	v_cndmask_b32_e32 v77, v228, v111, vcc
	s_and_b64 vcc, s[20:21], s[44:45]
	v_readlane_b32 s20, v254, 13
	v_fmac_f32_e32 v112, 0x3e000000, v78
	v_readlane_b32 s21, v254, 14
	v_cndmask_b32_e32 v78, v228, v112, vcc
	v_fmac_f32_e32 v113, 0x3e000000, v79
	s_and_b64 vcc, s[20:21], s[44:45]
	v_max3_f32 v99, v99, v98, v77
	v_cndmask_b32_e32 v76, v228, v113, vcc
	v_max3_f32 v99, v99, v78, v76
	v_add_u32_e32 v79, 0x8500, v152
	v_add_u32_e32 v102, 0x8508, v152
	v_add_u32_e32 v104, 0x8520, v152
	v_add_u32_e32 v106, 0x8528, v152
	ds_read2_b32 v[100:101], v79 offset1:1
	ds_read2_b32 v[102:103], v102 offset1:1
	ds_read2_b32 v[104:105], v104 offset1:1
	ds_read2_b32 v[106:107], v106 offset1:1
	v_readlane_b32 s20, v254, 15
	v_add_u32_e32 v79, 0x8540, v152
	v_add_u32_e32 v110, 0x8548, v152
	v_add_u32_e32 v112, 0x8560, v152
	v_add_u32_e32 v114, 0x8568, v152
	v_readlane_b32 s21, v254, 16
	ds_read2_b32 v[108:109], v79 offset1:1
	ds_read2_b32 v[110:111], v110 offset1:1
	ds_read2_b32 v[112:113], v112 offset1:1
	ds_read2_b32 v[114:115], v114 offset1:1
	s_waitcnt lgkmcnt(6)
	s_or_b64 vcc, s[44:45], s[20:21]
	v_readlane_b32 s20, v254, 17
	v_fmac_f32_e32 v100, 0x3e000000, v48
	v_readlane_b32 s21, v254, 18
	v_cndmask_b32_e32 v79, v228, v100, vcc
	s_or_b64 vcc, s[44:45], s[20:21]
	v_readlane_b32 s20, v254, 19
	v_fmac_f32_e32 v101, 0x3e000000, v49
	v_readlane_b32 s21, v254, 20
	v_cndmask_b32_e32 v49, v228, v101, vcc
	s_or_b64 vcc, s[44:45], s[20:21]
	v_readlane_b32 s20, v254, 21
	v_fmac_f32_e32 v102, 0x3e000000, v50
	v_readlane_b32 s21, v254, 22
	v_cndmask_b32_e32 v50, v228, v102, vcc
	s_or_b64 vcc, s[44:45], s[20:21]
	v_readlane_b32 s20, v254, 23
	v_fmac_f32_e32 v103, 0x3e000000, v51
	v_readlane_b32 s21, v254, 24
	s_waitcnt lgkmcnt(4)
	v_cndmask_b32_e32 v51, v228, v103, vcc
	s_or_b64 vcc, s[44:45], s[20:21]
	v_readlane_b32 s20, v254, 25
	v_fmac_f32_e32 v104, 0x3e000000, v52
	v_readlane_b32 s21, v254, 26
	v_cndmask_b32_e32 v52, v228, v104, vcc
	s_or_b64 vcc, s[44:45], s[20:21]
	v_readlane_b32 s20, v254, 27
	v_fmac_f32_e32 v105, 0x3e000000, v53
	v_readlane_b32 s21, v254, 28
	v_cndmask_b32_e32 v53, v228, v105, vcc
	s_or_b64 vcc, s[44:45], s[20:21]
	v_readlane_b32 s20, v254, 29
	v_fmac_f32_e32 v106, 0x3e000000, v54
	v_readlane_b32 s21, v254, 30
	v_max3_f32 v48, v99, v79, v49
	v_cndmask_b32_e32 v99, v228, v106, vcc
	s_or_b64 vcc, s[44:45], s[20:21]
	v_readlane_b32 s20, v254, 31
	v_fmac_f32_e32 v107, 0x3e000000, v55
	v_readlane_b32 s21, v254, 32
	s_waitcnt lgkmcnt(2)
	v_cndmask_b32_e32 v55, v228, v107, vcc
	s_or_b64 vcc, s[44:45], s[20:21]
	v_readlane_b32 s20, v254, 33
	v_fmac_f32_e32 v108, 0x3e000000, v56
	v_readlane_b32 s21, v254, 34
	v_cndmask_b32_e32 v56, v228, v108, vcc
	s_or_b64 vcc, s[44:45], s[20:21]
	v_readlane_b32 s20, v254, 35
	v_fmac_f32_e32 v109, 0x3e000000, v57
	v_readlane_b32 s21, v254, 36
	v_cndmask_b32_e32 v57, v228, v109, vcc
	s_or_b64 vcc, s[44:45], s[20:21]
	v_readlane_b32 s20, v254, 37
	v_fmac_f32_e32 v110, 0x3e000000, v58
	v_readlane_b32 s21, v254, 38
	v_cndmask_b32_e32 v58, v228, v110, vcc
	s_or_b64 vcc, s[44:45], s[20:21]
	v_readlane_b32 s20, v254, 39
	v_fmac_f32_e32 v111, 0x3e000000, v59
	v_readlane_b32 s21, v254, 40
	s_waitcnt lgkmcnt(0)
	v_cndmask_b32_e32 v59, v228, v111, vcc
	s_or_b64 vcc, s[44:45], s[20:21]
	v_readlane_b32 s20, v254, 41
	v_fmac_f32_e32 v112, 0x3e000000, v60
	v_readlane_b32 s21, v254, 42
	v_max3_f32 v48, v48, v50, v51
	v_cndmask_b32_e32 v100, v228, v112, vcc
	s_or_b64 vcc, s[44:45], s[20:21]
	v_readlane_b32 s20, v254, 43
	v_max3_f32 v48, v48, v52, v53
	v_fmac_f32_e32 v113, 0x3e000000, v61
	v_readlane_b32 s21, v254, 44
	v_max3_f32 v48, v48, v99, v55
	v_cndmask_b32_e32 v101, v228, v113, vcc
	s_or_b64 vcc, s[44:45], s[20:21]
	v_readlane_b32 s20, v254, 45
	v_max3_f32 v48, v48, v56, v57
	v_fmac_f32_e32 v114, 0x3e000000, v62
	v_readlane_b32 s21, v254, 46
	v_max3_f32 v48, v48, v58, v59
	v_cndmask_b32_e32 v62, v228, v114, vcc
	v_fmac_f32_e32 v115, 0x3e000000, v63
	s_or_b64 vcc, s[44:45], s[20:21]
	v_max3_f32 v48, v48, v100, v101
	v_cndmask_b32_e32 v60, v228, v115, vcc
	v_max3_f32 v48, v48, v62, v60
	v_add_u32_e32 v54, 0x8580, v152
	v_add_u32_e32 v108, 0x85a8, v152
	v_add_u32_e32 v61, 0x8588, v152
	v_add_u32_e32 v63, 0x85a0, v152
	ds_read2_b32 v[102:103], v54 offset1:1
	ds_read2_b32 v[104:105], v61 offset1:1
	ds_read2_b32 v[106:107], v63 offset1:1
	ds_read2_b32 v[108:109], v108 offset1:1
	v_readlane_b32 s20, v254, 47
	v_add_u32_e32 v54, 0x85c0, v152
	v_add_u32_e32 v116, 0x85e8, v152
	v_readlane_b32 s21, v254, 48
	v_add_u32_e32 v61, 0x85c8, v152
	v_add_u32_e32 v63, 0x85e0, v152
	ds_read2_b32 v[110:111], v54 offset1:1
	ds_read2_b32 v[112:113], v61 offset1:1
	ds_read2_b32 v[114:115], v63 offset1:1
	ds_read2_b32 v[116:117], v116 offset1:1
	s_waitcnt lgkmcnt(6)
	s_or_b64 vcc, s[44:45], s[20:21]
	v_readlane_b32 s20, v254, 49
	v_fmac_f32_e32 v102, 0x3e000000, v32
	v_readlane_b32 s21, v254, 50
	v_cndmask_b32_e32 v63, v228, v102, vcc
	s_or_b64 vcc, s[44:45], s[20:21]
	v_readlane_b32 s20, v254, 51
	v_fmac_f32_e32 v103, 0x3e000000, v33
	v_readlane_b32 s21, v254, 52
	v_cndmask_b32_e32 v102, v228, v103, vcc
	s_or_b64 vcc, s[44:45], s[20:21]
	v_readlane_b32 s20, v254, 53
	v_fmac_f32_e32 v104, 0x3e000000, v34
	v_readlane_b32 s21, v254, 54
	v_cndmask_b32_e32 v103, v228, v104, vcc
	s_or_b64 vcc, s[44:45], s[20:21]
	v_readlane_b32 s20, v254, 55
	v_fmac_f32_e32 v105, 0x3e000000, v35
	v_readlane_b32 s21, v254, 56
	s_waitcnt lgkmcnt(4)
	v_cndmask_b32_e32 v105, v228, v105, vcc
	s_or_b64 vcc, s[44:45], s[20:21]
	v_readlane_b32 s20, v254, 57
	v_fmac_f32_e32 v106, 0x3e000000, v36
	v_readlane_b32 s21, v254, 58
	v_cndmask_b32_e32 v106, v228, v106, vcc
	s_or_b64 vcc, s[44:45], s[20:21]
	v_readlane_b32 s20, v254, 59
	v_fmac_f32_e32 v107, 0x3e000000, v37
	v_readlane_b32 s21, v254, 60
	v_cndmask_b32_e32 v107, v228, v107, vcc
	s_or_b64 vcc, s[44:45], s[20:21]
	v_readlane_b32 s20, v254, 61
	v_fmac_f32_e32 v108, 0x3e000000, v38
	v_readlane_b32 s21, v254, 62
	v_cndmask_b32_e32 v38, v228, v108, vcc
	s_or_b64 vcc, s[44:45], s[20:21]
	v_readlane_b32 s20, v254, 63
	v_fmac_f32_e32 v109, 0x3e000000, v39
	v_readlane_b32 s21, v255, 0
	s_waitcnt lgkmcnt(2)
	v_cndmask_b32_e32 v118, v228, v109, vcc
	s_or_b64 vcc, s[44:45], s[20:21]
	v_readlane_b32 s20, v255, 1
	v_fmac_f32_e32 v110, 0x3e000000, v40
	v_readlane_b32 s21, v255, 2
	v_cndmask_b32_e32 v110, v228, v110, vcc
	s_or_b64 vcc, s[44:45], s[20:21]
	v_readlane_b32 s20, v255, 3
	v_fmac_f32_e32 v111, 0x3e000000, v41
	v_readlane_b32 s21, v255, 4
	v_cndmask_b32_e32 v119, v228, v111, vcc
	s_or_b64 vcc, s[44:45], s[20:21]
	v_readlane_b32 s20, v255, 5
	v_fmac_f32_e32 v112, 0x3e000000, v42
	v_readlane_b32 s21, v255, 6
	v_cndmask_b32_e32 v112, v228, v112, vcc
	s_or_b64 vcc, s[44:45], s[20:21]
	v_readlane_b32 s20, v255, 7
	v_fmac_f32_e32 v113, 0x3e000000, v43
	v_readlane_b32 s21, v255, 8
	s_waitcnt lgkmcnt(0)
	v_cndmask_b32_e32 v113, v228, v113, vcc
	s_or_b64 vcc, s[44:45], s[20:21]
	v_readlane_b32 s20, v255, 9
	v_max3_f32 v32, v48, v63, v102
	v_fmac_f32_e32 v114, 0x3e000000, v44
	v_readlane_b32 s21, v255, 10
	v_max3_f32 v32, v32, v103, v105
	v_cndmask_b32_e32 v120, v228, v114, vcc
	s_or_b64 vcc, s[44:45], s[20:21]
	v_readlane_b32 s20, v255, 11
	v_max3_f32 v32, v32, v106, v107
	v_fmac_f32_e32 v115, 0x3e000000, v45
	v_readlane_b32 s21, v255, 12
	v_max3_f32 v32, v32, v38, v118
	v_cndmask_b32_e32 v115, v228, v115, vcc
	s_or_b64 vcc, s[44:45], s[20:21]
	v_readlane_b32 s20, v255, 13
	v_max3_f32 v32, v32, v110, v119
	v_fmac_f32_e32 v116, 0x3e000000, v46
	v_readlane_b32 s21, v255, 14
	v_max3_f32 v32, v32, v112, v113
	v_cndmask_b32_e32 v116, v228, v116, vcc
	v_fmac_f32_e32 v117, 0x3e000000, v47
	s_or_b64 vcc, s[44:45], s[20:21]
	v_max3_f32 v32, v32, v120, v115
	v_cndmask_b32_e32 v117, v228, v117, vcc
	v_max3_f32 v39, v32, v116, v117
	v_add_u32_e32 v32, 0x8600, v152
	v_add_u32_e32 v34, 0x8608, v152
	v_add_u32_e32 v36, 0x8620, v152
	v_add_u32_e32 v40, 0x8628, v152
	ds_read2_b32 v[32:33], v32 offset1:1
	ds_read2_b32 v[34:35], v34 offset1:1
	ds_read2_b32 v[36:37], v36 offset1:1
	ds_read2_b32 v[40:41], v40 offset1:1
	v_readlane_b32 s20, v255, 15
	v_add_u32_e32 v42, 0x8640, v152
	v_add_u32_e32 v44, 0x8648, v152
	v_add_u32_e32 v46, 0x8660, v152
	v_readlane_b32 s21, v255, 16
	v_add_u32_e32 v48, 0x8668, v152
	ds_read2_b32 v[42:43], v42 offset1:1
	ds_read2_b32 v[44:45], v44 offset1:1
	ds_read2_b32 v[46:47], v46 offset1:1
	ds_read2_b32 v[108:109], v48 offset1:1
	s_waitcnt lgkmcnt(6)
	s_or_b64 vcc, s[44:45], s[20:21]
	v_readlane_b32 s20, v255, 17
	v_fmac_f32_e32 v32, 0x3e000000, v16
	v_readlane_b32 s21, v255, 18
	v_cndmask_b32_e32 v121, v228, v32, vcc
	s_or_b64 vcc, s[44:45], s[20:21]
	v_readlane_b32 s20, v255, 19
	v_fmac_f32_e32 v33, 0x3e000000, v17
	v_readlane_b32 s21, v255, 20
	v_cndmask_b32_e32 v139, v228, v33, vcc
	s_or_b64 vcc, s[44:45], s[20:21]
	v_readlane_b32 s20, v255, 21
	v_fmac_f32_e32 v34, 0x3e000000, v18
	v_readlane_b32 s21, v255, 22
	v_cndmask_b32_e32 v140, v228, v34, vcc
	s_or_b64 vcc, s[44:45], s[20:21]
	v_readlane_b32 s20, v255, 23
	v_fmac_f32_e32 v35, 0x3e000000, v19
	v_readlane_b32 s21, v255, 24
	s_waitcnt lgkmcnt(4)
	v_cndmask_b32_e32 v141, v228, v35, vcc
	s_or_b64 vcc, s[44:45], s[20:21]
	v_readlane_b32 s20, v255, 25
	v_fmac_f32_e32 v36, 0x3e000000, v20
	v_readlane_b32 s21, v255, 26
	v_cndmask_b32_e32 v167, v228, v36, vcc
	v_fmac_f32_e32 v37, 0x3e000000, v21
	s_or_b64 vcc, s[44:45], s[20:21]
	v_cndmask_b32_e32 v168, v228, v37, vcc
	v_fmac_f32_e32 v40, 0x3e000000, v22
	s_or_b64 vcc, s[44:45], s[58:59]
	s_waitcnt lgkmcnt(2)
	v_cndmask_b32_e32 v169, v228, v40, vcc
	v_fmac_f32_e32 v41, 0x3e000000, v23
	s_or_b64 vcc, s[44:45], s[60:61]
	v_cndmask_b32_e32 v170, v228, v41, vcc
	v_fmac_f32_e32 v42, 0x3e000000, v24
	s_or_b64 vcc, s[44:45], s[62:63]
	v_cndmask_b32_e32 v171, v228, v42, vcc
	v_fmac_f32_e32 v43, 0x3e000000, v25
	s_or_b64 vcc, s[44:45], s[64:65]
	v_max3_f32 v16, v39, v121, v139
	v_cndmask_b32_e32 v172, v228, v43, vcc
	v_fmac_f32_e32 v44, 0x3e000000, v26
	s_or_b64 vcc, s[44:45], s[66:67]
	s_waitcnt lgkmcnt(0)
	v_max3_f32 v16, v16, v140, v141
	v_cndmask_b32_e32 v173, v228, v44, vcc
	v_fmac_f32_e32 v45, 0x3e000000, v27
	s_or_b64 vcc, s[44:45], s[68:69]
	v_max3_f32 v16, v16, v167, v168
	v_cndmask_b32_e32 v174, v228, v45, vcc
	v_fmac_f32_e32 v46, 0x3e000000, v28
	s_or_b64 vcc, s[44:45], s[70:71]
	v_max3_f32 v16, v16, v169, v170
	v_cndmask_b32_e32 v175, v228, v46, vcc
	v_fmac_f32_e32 v47, 0x3e000000, v29
	s_or_b64 vcc, s[44:45], s[72:73]
	v_max3_f32 v16, v16, v171, v172
	v_cndmask_b32_e32 v176, v228, v47, vcc
	v_fmac_f32_e32 v108, 0x3e000000, v30
	s_or_b64 vcc, s[44:45], s[74:75]
	v_max3_f32 v16, v16, v173, v174
	v_cndmask_b32_e32 v108, v228, v108, vcc
	v_fmac_f32_e32 v109, 0x3e000000, v31
	s_or_b64 vcc, s[44:45], s[76:77]
	v_max3_f32 v16, v16, v175, v176
	v_cndmask_b32_e32 v177, v228, v109, vcc
	v_max3_f32 v32, v16, v108, v177
	v_add_u32_e32 v16, 0x8680, v152
	v_add_u32_e32 v18, 0x8688, v152
	v_add_u32_e32 v20, 0x86a0, v152
	v_add_u32_e32 v22, 0x86a8, v152
	ds_read2_b32 v[16:17], v16 offset1:1
	ds_read2_b32 v[18:19], v18 offset1:1
	ds_read2_b32 v[20:21], v20 offset1:1
	ds_read2_b32 v[22:23], v22 offset1:1
	v_add_u32_e32 v24, 0x86c0, v152
	v_add_u32_e32 v26, 0x86c8, v152
	v_add_u32_e32 v28, 0x86e0, v152
	v_add_u32_e32 v30, 0x86e8, v152
	ds_read2_b32 v[24:25], v24 offset1:1
	ds_read2_b32 v[26:27], v26 offset1:1
	ds_read2_b32 v[28:29], v28 offset1:1
	ds_read2_b32 v[30:31], v30 offset1:1
	s_waitcnt lgkmcnt(6)
	s_waitcnt lgkmcnt(4)
	s_waitcnt lgkmcnt(2)
	s_waitcnt lgkmcnt(0)
	v_fmac_f32_e32 v16, 0x3e000000, v0
	v_fmac_f32_e32 v17, 0x3e000000, v1
	v_cndmask_b32_e64 v16, v228, v16, s[78:79]
	v_cndmask_b32_e64 v17, v228, v17, s[80:81]
	v_fmac_f32_e32 v18, 0x3e000000, v2
	v_fmac_f32_e32 v19, 0x3e000000, v3
	v_max3_f32 v0, v32, v16, v17
	v_cndmask_b32_e64 v18, v228, v18, s[82:83]
	v_cndmask_b32_e64 v19, v228, v19, s[84:85]
	v_fmac_f32_e32 v20, 0x3e000000, v4
	v_fmac_f32_e32 v21, 0x3e000000, v5
	v_max3_f32 v0, v0, v18, v19
	v_cndmask_b32_e64 v20, v228, v20, s[86:87]
	v_cndmask_b32_e64 v21, v228, v21, s[88:89]
	v_fmac_f32_e32 v22, 0x3e000000, v6
	v_fmac_f32_e32 v23, 0x3e000000, v7
	v_max3_f32 v0, v0, v20, v21
	v_cndmask_b32_e64 v22, v228, v22, s[90:91]
	v_cndmask_b32_e64 v23, v228, v23, s[92:93]
	v_fmac_f32_e32 v24, 0x3e000000, v8
	v_fmac_f32_e32 v25, 0x3e000000, v9
	v_max3_f32 v0, v0, v22, v23
	v_cndmask_b32_e64 v24, v228, v24, s[94:95]
	v_cndmask_b32_e64 v9, v228, v25, s[96:97]
	v_fmac_f32_e32 v26, 0x3e000000, v10
	v_fmac_f32_e32 v27, 0x3e000000, v11
	v_max3_f32 v0, v0, v24, v9
	v_cndmask_b32_e64 v10, v228, v26, s[2:3]
	v_cndmask_b32_e64 v11, v228, v27, s[4:5]
	v_fmac_f32_e32 v28, 0x3e000000, v12
	v_fmac_f32_e32 v29, 0x3e000000, v13
	v_max3_f32 v0, v0, v10, v11
	v_cndmask_b32_e64 v12, v228, v28, s[6:7]
	v_cndmask_b32_e64 v13, v228, v29, s[8:9]
	v_fmac_f32_e32 v30, 0x3e000000, v14
	v_fmac_f32_e32 v31, 0x3e000000, v15
	v_max3_f32 v0, v0, v12, v13
	v_cndmask_b32_e64 v14, v228, v30, s[10:11]
	v_cndmask_b32_e64 v15, v228, v31, s[12:13]
	v_max3_f32 v0, v0, v14, v15
	v_mov_b32_e32 v1, v0
	s_nop 1
	v_permlane32_swap_b32_e32 v0, v1
	s_waitcnt lgkmcnt(0)
	v_max3_f32 v0, v0, v1, v137
	v_sub_f32_e32 v25, v72, v0
	v_mul_f32_e32 v25, 0x3fb8aa3b, v25
	v_exp_f32_e32 v32, v25
	v_sub_f32_e32 v25, v73, v0
	v_mul_f32_e32 v25, 0x3fb8aa3b, v25
	v_exp_f32_e32 v33, v25
	v_sub_f32_e32 v25, v74, v0
	v_mul_f32_e32 v25, 0x3fb8aa3b, v25
	v_exp_f32_e32 v35, v25
	v_sub_f32_e32 v25, v75, v0
	v_mul_f32_e32 v25, 0x3fb8aa3b, v25
	v_sub_f32_e32 v1, v64, v0
	v_exp_f32_e32 v37, v25
	v_sub_f32_e32 v25, v98, v0
	v_sub_f32_e32 v2, v65, v0
	v_mul_f32_e32 v1, 0x3fb8aa3b, v1
	v_mul_f32_e32 v25, 0x3fb8aa3b, v25
	v_sub_f32_e32 v3, v66, v0
	v_mul_f32_e32 v2, 0x3fb8aa3b, v2
	v_exp_f32_e32 v1, v1
	v_exp_f32_e32 v40, v25
	v_sub_f32_e32 v25, v77, v0
	v_exp_f32_e32 v2, v2
	v_mul_f32_e32 v3, 0x3fb8aa3b, v3
	v_sub_f32_e32 v4, v67, v0
	v_mul_f32_e32 v25, 0x3fb8aa3b, v25
	v_exp_f32_e32 v3, v3
	v_mul_f32_e32 v4, 0x3fb8aa3b, v4
	v_sub_f32_e32 v5, v68, v0
	v_exp_f32_e32 v45, v25
	v_sub_f32_e32 v25, v78, v0
	v_exp_f32_e32 v4, v4
	v_mul_f32_e32 v5, 0x3fb8aa3b, v5
	v_sub_f32_e32 v6, v69, v0
	v_mul_f32_e32 v25, 0x3fb8aa3b, v25
	v_exp_f32_e32 v5, v5
	v_mul_f32_e32 v6, 0x3fb8aa3b, v6
	v_sub_f32_e32 v7, v70, v0
	v_exp_f32_e32 v48, v25
	v_add_f32_e32 v25, 0, v1
	v_exp_f32_e32 v6, v6
	v_mul_f32_e32 v7, 0x3fb8aa3b, v7
	v_sub_f32_e32 v8, v71, v0
	v_add_f32_e32 v25, v2, v25
	v_exp_f32_e32 v7, v7
	v_mul_f32_e32 v8, 0x3fb8aa3b, v8
	v_add_f32_e32 v25, v3, v25
	v_exp_f32_e32 v8, v8
	v_add_f32_e32 v25, v4, v25
	v_add_f32_e32 v25, v5, v25
	v_add_f32_e32 v25, v6, v25
	v_add_f32_e32 v25, v7, v25
	v_add_f32_e32 v25, v8, v25
	v_add_f32_e32 v25, v32, v25
	v_add_f32_e32 v25, v33, v25
	v_sub_f32_e32 v26, v76, v0
	v_add_f32_e32 v25, v35, v25
	v_mul_f32_e32 v26, 0x3fb8aa3b, v26
	v_add_f32_e32 v25, v37, v25
	v_exp_f32_e32 v109, v26
	v_add_f32_e32 v25, v40, v25
	v_add_f32_e32 v25, v45, v25
	v_add_f32_e32 v25, v48, v25
	v_add_f32_e32 v25, v109, v25
	v_sub_f32_e32 v26, v79, v0
	v_mul_f32_e32 v26, 0x3fb8aa3b, v26
	v_exp_f32_e32 v42, v26
	v_sub_f32_e32 v26, v49, v0
	v_mul_f32_e32 v26, 0x3fb8aa3b, v26
	v_exp_f32_e32 v49, v26
	v_sub_f32_e32 v26, v50, v0
	v_mul_f32_e32 v26, 0x3fb8aa3b, v26
	v_exp_f32_e32 v54, v26
	v_sub_f32_e32 v26, v51, v0
	v_mul_f32_e32 v26, 0x3fb8aa3b, v26
	v_exp_f32_e32 v61, v26
	v_sub_f32_e32 v26, v52, v0
	v_mul_f32_e32 v26, 0x3fb8aa3b, v26
	v_exp_f32_e32 v67, v26
	v_sub_f32_e32 v26, v53, v0
	v_mul_f32_e32 v26, 0x3fb8aa3b, v26
	v_exp_f32_e32 v74, v26
	v_sub_f32_e32 v26, v99, v0
	v_mul_f32_e32 v26, 0x3fb8aa3b, v26
	v_exp_f32_e32 v79, v26
	v_sub_f32_e32 v26, v55, v0
	v_mul_f32_e32 v26, 0x3fb8aa3b, v26
	v_exp_f32_e32 v104, v26
	v_sub_f32_e32 v26, v56, v0
	v_mul_f32_e32 v26, 0x3fb8aa3b, v26
	v_exp_f32_e32 v34, v26
	v_sub_f32_e32 v26, v57, v0
	v_mul_f32_e32 v26, 0x3fb8aa3b, v26
	v_exp_f32_e32 v36, v26
	v_sub_f32_e32 v26, v58, v0
	v_mul_f32_e32 v26, 0x3fb8aa3b, v26
	v_add_f32_e32 v25, v42, v25
	v_exp_f32_e32 v39, v26
	v_sub_f32_e32 v26, v59, v0
	v_add_f32_e32 v25, v49, v25
	v_mul_f32_e32 v26, 0x3fb8aa3b, v26
	v_add_f32_e32 v25, v54, v25
	v_exp_f32_e32 v43, v26
	v_sub_f32_e32 v26, v100, v0
	v_add_f32_e32 v25, v61, v25
	v_mul_f32_e32 v26, 0x3fb8aa3b, v26
	v_add_f32_e32 v25, v67, v25
	v_exp_f32_e32 v47, v26
	v_sub_f32_e32 v26, v101, v0
	v_add_f32_e32 v25, v74, v25
	v_mul_f32_e32 v26, 0x3fb8aa3b, v26
	v_add_f32_e32 v25, v79, v25
	v_exp_f32_e32 v55, v26
	v_sub_f32_e32 v26, v62, v0
	v_add_f32_e32 v25, v104, v25
	v_mul_f32_e32 v26, 0x3fb8aa3b, v26
	v_add_f32_e32 v25, v34, v25
	v_exp_f32_e32 v58, v26
	v_add_f32_e32 v25, v36, v25
	v_sub_f32_e32 v26, v60, v0
	v_add_f32_e32 v25, v39, v25
	v_mul_f32_e32 v26, 0x3fb8aa3b, v26
	v_add_f32_e32 v25, v43, v25
	v_exp_f32_e32 v114, v26
	v_add_f32_e32 v25, v47, v25
	v_add_f32_e32 v25, v55, v25
	v_add_f32_e32 v25, v58, v25
	v_add_f32_e32 v25, v114, v25
	v_sub_f32_e32 v26, v63, v0
	v_mul_f32_e32 v26, 0x3fb8aa3b, v26
	v_exp_f32_e32 v51, v26
	v_sub_f32_e32 v26, v102, v0
	v_mul_f32_e32 v26, 0x3fb8aa3b, v26
	v_exp_f32_e32 v59, v26
	v_sub_f32_e32 v26, v103, v0
	v_mul_f32_e32 v26, 0x3fb8aa3b, v26
	v_exp_f32_e32 v64, v26
	v_sub_f32_e32 v26, v105, v0
	v_mul_f32_e32 v26, 0x3fb8aa3b, v26
	v_exp_f32_e32 v71, v26
	v_sub_f32_e32 v26, v106, v0
	v_mul_f32_e32 v26, 0x3fb8aa3b, v26
	v_exp_f32_e32 v77, v26
	v_sub_f32_e32 v26, v107, v0
	v_mul_f32_e32 v26, 0x3fb8aa3b, v26
	v_exp_f32_e32 v101, v26
	v_sub_f32_e32 v26, v38, v0
	v_mul_f32_e32 v26, 0x3fb8aa3b, v26
	v_exp_f32_e32 v106, v26
	v_sub_f32_e32 v26, v118, v0
	v_mul_f32_e32 v26, 0x3fb8aa3b, v26
	v_exp_f32_e32 v111, v26
	v_sub_f32_e32 v26, v110, v0
	v_mul_f32_e32 v26, 0x3fb8aa3b, v26
	v_exp_f32_e32 v38, v26
	v_sub_f32_e32 v26, v119, v0
	v_mul_f32_e32 v26, 0x3fb8aa3b, v26
	v_exp_f32_e32 v41, v26
	v_sub_f32_e32 v26, v112, v0
	v_mul_f32_e32 v26, 0x3fb8aa3b, v26
	v_add_f32_e32 v25, v51, v25
	v_exp_f32_e32 v46, v26
	v_sub_f32_e32 v26, v113, v0
	v_add_f32_e32 v25, v59, v25
	v_mul_f32_e32 v26, 0x3fb8aa3b, v26
	v_add_f32_e32 v25, v64, v25
	v_exp_f32_e32 v52, v26
	v_sub_f32_e32 v26, v120, v0
	v_add_f32_e32 v25, v71, v25
	v_mul_f32_e32 v26, 0x3fb8aa3b, v26
	v_add_f32_e32 v25, v77, v25
	v_exp_f32_e32 v57, v26
	v_sub_f32_e32 v26, v115, v0
	v_add_f32_e32 v25, v101, v25
	v_mul_f32_e32 v26, 0x3fb8aa3b, v26
	v_add_f32_e32 v25, v106, v25
	v_exp_f32_e32 v65, v26
	v_sub_f32_e32 v26, v116, v0
	v_add_f32_e32 v25, v111, v25
	v_mul_f32_e32 v26, 0x3fb8aa3b, v26
	v_add_f32_e32 v25, v38, v25
	v_exp_f32_e32 v69, v26
	v_add_f32_e32 v25, v41, v25
	v_sub_f32_e32 v26, v117, v0
	v_add_f32_e32 v25, v46, v25
	v_mul_f32_e32 v26, 0x3fb8aa3b, v26
	v_add_f32_e32 v25, v52, v25
	v_exp_f32_e32 v118, v26
	v_add_f32_e32 v25, v57, v25
	v_add_f32_e32 v25, v65, v25
	v_add_f32_e32 v25, v69, v25
	v_add_f32_e32 v25, v118, v25
	v_sub_f32_e32 v26, v121, v0
	v_mul_f32_e32 v26, 0x3fb8aa3b, v26
	v_exp_f32_e32 v62, v26
	v_sub_f32_e32 v26, v139, v0
	v_mul_f32_e32 v26, 0x3fb8aa3b, v26
	v_exp_f32_e32 v70, v26
	v_sub_f32_e32 v26, v140, v0
	v_mul_f32_e32 v26, 0x3fb8aa3b, v26
	v_exp_f32_e32 v75, v26
	v_sub_f32_e32 v26, v141, v0
	v_mul_f32_e32 v26, 0x3fb8aa3b, v26
	v_exp_f32_e32 v100, v26
	v_sub_f32_e32 v26, v167, v0
	v_mul_f32_e32 v26, 0x3fb8aa3b, v26
	v_exp_f32_e32 v105, v26
	v_sub_f32_e32 v26, v168, v0
	v_mul_f32_e32 v26, 0x3fb8aa3b, v26
	v_exp_f32_e32 v110, v26
	v_sub_f32_e32 v26, v169, v0
	v_mul_f32_e32 v26, 0x3fb8aa3b, v26
	v_exp_f32_e32 v113, v26
	v_sub_f32_e32 v26, v170, v0
	v_mul_f32_e32 v26, 0x3fb8aa3b, v26
	v_exp_f32_e32 v116, v26
	v_sub_f32_e32 v26, v171, v0
	v_mul_f32_e32 v26, 0x3fb8aa3b, v26
	v_exp_f32_e32 v44, v26
	v_sub_f32_e32 v26, v172, v0
	v_mul_f32_e32 v26, 0x3fb8aa3b, v26
	v_exp_f32_e32 v50, v26
	v_sub_f32_e32 v26, v173, v0
	v_mul_f32_e32 v26, 0x3fb8aa3b, v26
	v_add_f32_e32 v25, v62, v25
	v_exp_f32_e32 v56, v26
	v_sub_f32_e32 v26, v174, v0
	v_add_f32_e32 v25, v70, v25
	v_mul_f32_e32 v26, 0x3fb8aa3b, v26
	v_add_f32_e32 v25, v75, v25
	v_exp_f32_e32 v63, v26
	v_sub_f32_e32 v26, v175, v0
	v_add_f32_e32 v25, v100, v25
	v_mul_f32_e32 v26, 0x3fb8aa3b, v26
	v_add_f32_e32 v25, v105, v25
	v_exp_f32_e32 v68, v26
	v_sub_f32_e32 v26, v176, v0
	v_add_f32_e32 v25, v110, v25
	v_mul_f32_e32 v26, 0x3fb8aa3b, v26
	v_add_f32_e32 v25, v113, v25
	v_exp_f32_e32 v76, v26
	v_sub_f32_e32 v26, v108, v0
	v_add_f32_e32 v25, v116, v25
	v_mul_f32_e32 v26, 0x3fb8aa3b, v26
	v_add_f32_e32 v25, v44, v25
	v_exp_f32_e32 v98, v26
	v_add_f32_e32 v25, v50, v25
	v_sub_f32_e32 v26, v177, v0
	v_add_f32_e32 v25, v56, v25
	v_mul_f32_e32 v26, 0x3fb8aa3b, v26
	v_add_f32_e32 v25, v63, v25
	v_exp_f32_e32 v120, v26
	v_add_f32_e32 v25, v68, v25
	v_add_f32_e32 v25, v76, v25
	v_add_f32_e32 v25, v98, v25
	v_add_f32_e32 v25, v120, v25
	v_sub_f32_e32 v16, v16, v0
	v_mul_f32_e32 v16, 0x3fb8aa3b, v16
	v_exp_f32_e32 v72, v16
	v_sub_f32_e32 v16, v17, v0
	v_sub_f32_e32 v9, v9, v0
	v_mul_f32_e32 v16, 0x3fb8aa3b, v16
	v_mul_f32_e32 v9, 0x3fb8aa3b, v9
	v_exp_f32_e32 v99, v16
	v_sub_f32_e32 v16, v18, v0
	v_exp_f32_e32 v60, v9
	v_sub_f32_e32 v9, v10, v0
	v_mul_f32_e32 v16, 0x3fb8aa3b, v16
	v_mul_f32_e32 v9, 0x3fb8aa3b, v9
	v_exp_f32_e32 v102, v16
	v_sub_f32_e32 v16, v19, v0
	v_exp_f32_e32 v66, v9
	v_sub_f32_e32 v9, v11, v0
	v_mul_f32_e32 v16, 0x3fb8aa3b, v16
	v_mul_f32_e32 v9, 0x3fb8aa3b, v9
	v_exp_f32_e32 v108, v16
	v_sub_f32_e32 v16, v20, v0
	v_exp_f32_e32 v73, v9
	v_sub_f32_e32 v9, v12, v0
	v_mul_f32_e32 v16, 0x3fb8aa3b, v16
	v_mul_f32_e32 v9, 0x3fb8aa3b, v9
	v_exp_f32_e32 v112, v16
	v_sub_f32_e32 v16, v21, v0
	v_exp_f32_e32 v78, v9
	v_sub_f32_e32 v9, v13, v0
	v_mul_f32_e32 v16, 0x3fb8aa3b, v16
	v_mul_f32_e32 v9, 0x3fb8aa3b, v9
	v_exp_f32_e32 v115, v16
	v_sub_f32_e32 v16, v22, v0
	v_exp_f32_e32 v103, v9
	v_sub_f32_e32 v9, v14, v0
	v_mul_f32_e32 v16, 0x3fb8aa3b, v16
	v_mul_f32_e32 v9, 0x3fb8aa3b, v9
	v_exp_f32_e32 v117, v16
	v_sub_f32_e32 v16, v23, v0
	v_exp_f32_e32 v107, v9
	v_add_f32_e32 v9, v72, v25
	v_mul_f32_e32 v16, 0x3fb8aa3b, v16
	v_add_f32_e32 v9, v99, v9
	v_exp_f32_e32 v119, v16
	v_sub_f32_e32 v16, v24, v0
	v_add_f32_e32 v9, v102, v9
	v_mul_f32_e32 v16, 0x3fb8aa3b, v16
	v_add_f32_e32 v9, v108, v9
	v_exp_f32_e32 v53, v16
	v_add_f32_e32 v9, v112, v9
	v_add_f32_e32 v9, v115, v9
	v_add_f32_e32 v9, v117, v9
	v_add_f32_e32 v9, v119, v9
	v_add_f32_e32 v9, v53, v9
	v_add_f32_e32 v9, v60, v9
	v_sub_f32_e32 v10, v15, v0
	v_add_f32_e32 v9, v66, v9
	v_mul_f32_e32 v10, 0x3fb8aa3b, v10
	v_add_f32_e32 v9, v73, v9
	v_exp_f32_e32 v121, v10
	v_add_f32_e32 v9, v78, v9
	v_add_f32_e32 v9, v103, v9
	v_add_f32_e32 v9, v107, v9
	v_add_f32_e32 v9, v121, v9
	v_mov_b32_e32 v10, v9
	s_nop 1
	v_permlane32_swap_b32_e32 v9, v10
	s_and_saveexec_b64 s[20:21], s[14:15]
	s_cbranch_execz .LBB0_470
	s_mov_b32 s23, 0x1000706
	s_waitcnt vmcnt(0)
	v_perm_b32 v11, v94, v95, s23
	v_perm_b32 v95, v95, v96, s23
	v_perm_b32 v96, v96, v97, s23
	v_perm_b32 v97, v97, v94, s23
	v_mov_b32_e32 v94, v11
